# FF1 GEMM k-loop software-pipelined across the barrier: next k-tile fragments prefetched under 2nd MFMA group, a-high fragments under 1st group (on top of v27)
# speedup vs baseline: 1.0074x; 1.0074x over previous
; #define GEMM_DMA(kt) { GEMM_DMA_A(kt) GEMM_DMA_B(kt) }
; template <int EPI>
; __device__ __forceinline__ void gemm_tile_dma(const bft* __restrict__ A, int lda, const bft* __restrict__ Bt, int K, int row0, int col0,
;                                               char* smem, const EpiArgs& e) {
;     ...
;   f32x4 accL[4][4], accH[4][4];
; #pragma unroll
;   for (int i = 0; i < 4; ++i)
; #pragma unroll
;     for (int j = 0; j < 4; ++j) { accL[i][j] = (f32x4){0.f, 0.f, 0.f, 0.f}; accH[i][j] = (f32x4){0.f, 0.f, 0.f, 0.f}; }
;   const int lr = tid >> 2, pc = tid & 3;
;   const int kcs = (pc ^ ((4 - ((lr >> 2) & 3)) & 3)) * 8;
;   const int rco = (g ^ ((4 - ((r16 >> 2) & 3)) & 3)) * 8;
;   const bft* ag = A + (size_t)(row0 + lr) * lda + kcs;
;   const bft* bg = Bt + (size_t)(col0 + lr) * K + kcs;
;   const unsigned lds_a = (unsigned)(size_t)smem + (unsigned)(((wm * 128 + r16) * 32 + rco) * 2);
;   const unsigned lds_b = (unsigned)(size_t)smem + 16384u + (unsigned)(((wn * 64 + r16) * 32 + rco) * 2);
;   const int nk = K / 32;
;     ...
;   GEMM_DMA(0);
;   GEMM_DMA(1);
;   GEMM_DMA(2);
;   for (int kt = 0; kt < nk; ++kt) {
;     if (kt + 2 < nk) asm volatile("s_waitcnt vmcnt(8)" ::: "memory");
;     else if (kt + 1 < nk) asm volatile("s_waitcnt vmcnt(4)" ::: "memory");
;     else asm volatile("s_waitcnt vmcnt(0)" ::: "memory");
;     __builtin_amdgcn_s_barrier();
;     asm volatile("" ::: "memory");
;     const bool pf = kt + 3 < nk;
;     const unsigned so = (unsigned)(kt & 3) * GST;
;     bf16x8 a0, a1, a2, a3, b0, b1, b2, b3;
.LBB0_1311:
	s_lshr_b32 s13, s14, 4
	s_and_b32 s12, s14, 0x7f
	s_and_b32 s13, s13, 56
	s_cmpk_lt_u32 s14, 0x200
	s_cselect_b32 s15, 7, 1
	s_cselect_b32 s16, 3, 1
	s_and_b32 s15, s15, s14
	v_mov_b32_e32 v182, v196
	s_add_i32 s15, s3, s15
	s_add_i32 s15, s15, s13
	v_lshrrev_b32_e32 v0, 4, v182
	v_sub_u32_e32 v10, 0, v0
	v_lshlrev_b32_e32 v0, 2, v182
	s_lshl_b32 s15, s15, 8
	v_ashrrev_i32_e32 v4, 2, v182
	v_and_b32_e32 v0, 48, v0
	v_sub_u32_e32 v11, 0, v0
	v_add_u32_e32 v0, s15, v4
	v_xor_b32_e32 v5, v182, v10
	v_ashrrev_i32_e32 v1, 31, v0
	s_lshr_b32 s12, s12, s16
	v_lshlrev_b64 v[0:1], 11, v[0:1]
	v_lshlrev_b32_e32 v5, 4, v5
	v_lshlrev_b32_e32 v184, 4, v182
	s_lshl_b32 s16, s12, 8
	v_lshl_add_u64 v[2:3], s[62:63], 0, v[0:1]
	v_and_b32_e32 v160, 48, v5
	v_readfirstlane_b32 s12, v184
	v_add_u32_e32 v14, 0x2000, v184
	v_lshl_add_u64 v[2:3], v[2:3], 0, v[160:161]
	v_add_u32_e32 v4, s16, v4
	v_ashrrev_i32_e32 v8, 1, v182
	s_mov_b32 m0, s12
	s_mov_b64 s[38:39], 0x40000
	v_readfirstlane_b32 s12, v14
	v_ashrrev_i32_e32 v5, 31, v4
	v_and_b32_e32 v183, 0xffffff80, v8
	global_load_lds_dwordx4 v[2:3], off
	v_lshl_add_u64 v[8:9], v[2:3], 0, s[38:39]
	s_mov_b32 m0, s12
	v_lshlrev_b64 v[4:5], 11, v[4:5]
	global_load_lds_dwordx4 v[8:9], off
	v_add_u32_e32 v8, 0x4000, v184
	v_lshl_add_u64 v[6:7], s[24:25], 0, v[4:5]
	v_readfirstlane_b32 s12, v8
	v_add_u32_e32 v14, 0x6000, v184
	v_lshl_add_u64 v[6:7], v[6:7], 0, v[160:161]
	s_mov_b32 m0, s12
	v_readfirstlane_b32 s12, v14
	v_add_u32_e32 v14, 0x8000, v184
	global_load_lds_dwordx4 v[6:7], off
	v_lshl_add_u64 v[8:9], v[6:7], 0, s[38:39]
	s_mov_b32 m0, s12
	v_readfirstlane_b32 s12, v14
	v_add_u32_e32 v14, 0xa000, v184
	global_load_lds_dwordx4 v[8:9], off
	v_lshl_add_u64 v[8:9], v[2:3], 0, 64
	s_mov_b32 m0, s12
	s_mov_b64 s[38:39], 0x40040
	v_readfirstlane_b32 s12, v14
	v_add_u32_e32 v14, 0xc000, v184
	global_load_lds_dwordx4 v[8:9], off
	v_lshl_add_u64 v[8:9], v[2:3], 0, s[38:39]
	s_mov_b32 m0, s12
	v_readfirstlane_b32 s12, v14
	v_add_u32_e32 v14, 0xe000, v184
	global_load_lds_dwordx4 v[8:9], off
	v_lshl_add_u64 v[8:9], v[6:7], 0, 64
	s_mov_b32 m0, s12
	v_readfirstlane_b32 s12, v14
	v_add_u32_e32 v14, 0x10000, v184
	global_load_lds_dwordx4 v[8:9], off
	v_lshl_add_u64 v[8:9], v[6:7], 0, s[38:39]
	s_mov_b32 m0, s12
	s_mov_b64 s[38:39], 0x80
	v_readfirstlane_b32 s12, v14
	global_load_lds_dwordx4 v[8:9], off
	v_lshl_add_u64 v[8:9], v[2:3], 0, s[38:39]
	s_mov_b32 m0, s12
	s_mov_b64 s[40:41], 0x40080
	global_load_lds_dwordx4 v[8:9], off
	v_add_u32_e32 v8, 0x12000, v184
	v_lshl_add_u64 v[2:3], v[2:3], 0, s[40:41]
	v_readfirstlane_b32 s12, v8
	v_add_u32_e32 v8, 0x14000, v184
	s_mov_b32 m0, s12
	v_readfirstlane_b32 s12, v8
	global_load_lds_dwordx4 v[2:3], off
	v_lshl_add_u64 v[2:3], v[6:7], 0, s[38:39]
	s_mov_b32 m0, s12
	v_lshlrev_b32_e32 v13, 6, v182
	global_load_lds_dwordx4 v[2:3], off
	v_lshl_add_u64 v[2:3], v[6:7], 0, s[40:41]
	v_add_u32_e32 v6, 0x16000, v184
	v_bitop3_b32 v11, v182, 48, v11 bitop3:0x48
	v_readfirstlane_b32 s12, v6
	s_mov_b32 m0, s12
	v_and_b32_e32 v180, 15, v182
	global_load_lds_dwordx4 v[2:3], off
	v_and_b32_e32 v2, 0x33c0, v13
	v_or3_b32 v133, v2, v11, s42
	v_bitop3_b32 v2, v182, 3, v10 bitop3:0x48
	v_lshlrev_b32_e32 v2, 4, v2
	v_or_b32_e32 v0, v0, v2
	v_or_b32_e32 v12, v183, v180
	v_or_b32_e32 v4, v4, v2
	s_waitcnt vmcnt(0)
	v_lshl_add_u64 v[130:131], s[90:91], 0, v[0:1]
	v_mov_b32_e32 v0, 0
	v_not_b32_e32 v252, 63
	v_mov_b32_e32 v251, 0x42800000
	v_mov_b32_e32 v250, 0x22000
	s_mov_b32 s17, 0
	v_lshl_or_b32 v132, v12, 6, v11
	v_lshl_add_u64 v[128:129], s[90:91], 0, v[4:5]
	s_mov_b64 s[12:13], 0
	v_mov_b32_e32 v1, v0
	v_mov_b32_e32 v2, v0
	v_mov_b32_e32 v3, v0
	v_mov_b32_e32 v32, v0
	v_mov_b32_e32 v33, v0
	v_mov_b32_e32 v34, v0
	v_mov_b32_e32 v35, v0
	v_mov_b32_e32 v28, v0
	v_mov_b32_e32 v29, v0
	v_mov_b32_e32 v30, v0
	v_mov_b32_e32 v31, v0
	v_mov_b32_e32 v36, v0
	v_mov_b32_e32 v37, v0
	v_mov_b32_e32 v38, v0
	v_mov_b32_e32 v39, v0
	v_mov_b32_e32 v24, v0
	v_mov_b32_e32 v25, v0
	v_mov_b32_e32 v26, v0
	v_mov_b32_e32 v27, v0
	v_mov_b32_e32 v40, v0
	v_mov_b32_e32 v41, v0
	v_mov_b32_e32 v42, v0
	v_mov_b32_e32 v43, v0
	v_mov_b32_e32 v20, v0
	v_mov_b32_e32 v21, v0
	v_mov_b32_e32 v22, v0
	v_mov_b32_e32 v23, v0
	v_mov_b32_e32 v44, v0
	v_mov_b32_e32 v45, v0
	v_mov_b32_e32 v46, v0
	v_mov_b32_e32 v47, v0
	v_mov_b32_e32 v16, v0
	v_mov_b32_e32 v17, v0
	v_mov_b32_e32 v18, v0
	v_mov_b32_e32 v19, v0
	v_mov_b32_e32 v48, v0
	v_mov_b32_e32 v49, v0
	v_mov_b32_e32 v50, v0
	v_mov_b32_e32 v51, v0
	v_mov_b32_e32 v12, v0
	v_mov_b32_e32 v13, v0
	v_mov_b32_e32 v14, v0
	v_mov_b32_e32 v15, v0
	v_mov_b32_e32 v52, v0
	v_mov_b32_e32 v53, v0
	v_mov_b32_e32 v54, v0
	v_mov_b32_e32 v55, v0
	v_mov_b32_e32 v8, v0
	v_mov_b32_e32 v9, v0
	v_mov_b32_e32 v10, v0
	v_mov_b32_e32 v11, v0
	v_mov_b32_e32 v56, v0
	v_mov_b32_e32 v57, v0
	v_mov_b32_e32 v58, v0
	v_mov_b32_e32 v59, v0
	v_mov_b32_e32 v4, v0
	v_mov_b32_e32 v5, v0
	v_mov_b32_e32 v6, v0
	v_mov_b32_e32 v7, v0
	v_mov_b32_e32 v60, v0
	v_mov_b32_e32 v61, v0
	v_mov_b32_e32 v62, v0
	v_mov_b32_e32 v63, v0
	v_mov_b32_e32 v64, v0
	v_mov_b32_e32 v65, v0
	v_mov_b32_e32 v66, v0
	v_mov_b32_e32 v67, v0
	v_mov_b32_e32 v68, v0
	v_mov_b32_e32 v69, v0
	v_mov_b32_e32 v70, v0
	v_mov_b32_e32 v71, v0
	v_mov_b32_e32 v72, v0
	v_mov_b32_e32 v73, v0
	v_mov_b32_e32 v74, v0
	v_mov_b32_e32 v75, v0
	v_mov_b32_e32 v76, v0
	v_mov_b32_e32 v77, v0
	v_mov_b32_e32 v78, v0
	v_mov_b32_e32 v79, v0
	v_mov_b32_e32 v80, v0
	v_mov_b32_e32 v81, v0
	v_mov_b32_e32 v82, v0
	v_mov_b32_e32 v83, v0
	v_mov_b32_e32 v84, v0
	v_mov_b32_e32 v85, v0
	v_mov_b32_e32 v86, v0
	v_mov_b32_e32 v87, v0
	v_mov_b32_e32 v88, v0
	v_mov_b32_e32 v89, v0
	v_mov_b32_e32 v90, v0
	v_mov_b32_e32 v91, v0
	v_mov_b32_e32 v92, v0
	v_mov_b32_e32 v93, v0
	v_mov_b32_e32 v94, v0
	v_mov_b32_e32 v95, v0
	v_mov_b32_e32 v96, v0
	v_mov_b32_e32 v97, v0
	v_mov_b32_e32 v98, v0
	v_mov_b32_e32 v99, v0
	v_mov_b32_e32 v100, v0
	v_mov_b32_e32 v101, v0
	v_mov_b32_e32 v102, v0
	v_mov_b32_e32 v103, v0
	v_mov_b32_e32 v104, v0
	v_mov_b32_e32 v105, v0
	v_mov_b32_e32 v106, v0
	v_mov_b32_e32 v107, v0
	v_mov_b32_e32 v108, v0
	v_mov_b32_e32 v109, v0
	v_mov_b32_e32 v110, v0
	v_mov_b32_e32 v111, v0
	v_mov_b32_e32 v116, v0
	v_mov_b32_e32 v117, v0
	v_mov_b32_e32 v118, v0
	v_mov_b32_e32 v119, v0
	v_mov_b32_e32 v120, v0
	v_mov_b32_e32 v121, v0
	v_mov_b32_e32 v122, v0
	v_mov_b32_e32 v123, v0
	v_mov_b32_e32 v124, v0
	v_mov_b32_e32 v125, v0
	v_mov_b32_e32 v126, v0
	v_mov_b32_e32 v127, v0
	v_mov_b32_e32 v112, v0
	v_mov_b32_e32 v113, v0
	v_mov_b32_e32 v114, v0
	v_mov_b32_e32 v115, v0
	s_and_b32 s27, s17, 0x18000
	v_add_u32_e32 v158, s27, v132
	v_or_b32_e32 v159, s27, v133
	s_waitcnt vmcnt(8)
	s_barrier
	ds_read_b128 v[134:137], v158
	ds_read_b128 v[138:141], v158 offset:1024
	ds_read_b128 v[142:145], v158 offset:2048
	ds_read_b128 v[146:149], v158 offset:3072
	ds_read_b128 v[150:153], v159
	ds_read_b128 v[154:157], v159 offset:1024
	ds_read_b128 v[162:165], v159 offset:2048
	ds_read_b128 v[166:169], v159 offset:3072
; #define ROW4(accv, r, av)                                                                              \
;     accv[r][0] = MFMA16(av, b0, accv[r][0]); accv[r][1] = MFMA16(av, b1, accv[r][1]);                      \
;     accv[r][2] = MFMA16(av, b2, accv[r][2]); accv[r][3] = MFMA16(av, b3, accv[r][3]);
; template <int EPI>
; __device__ __forceinline__ void gemm_tile_dma(const bft* __restrict__ A, int lda, const bft* __restrict__ Bt, int K, int row0, int col0,
;                                               char* smem, const EpiArgs& e) {
;     ...
;   for (int kt = 0; kt < nk; ++kt) {
;     if (kt + 2 < nk) asm volatile("s_waitcnt vmcnt(8)" ::: "memory");
;     else if (kt + 1 < nk) asm volatile("s_waitcnt vmcnt(4)" ::: "memory");
;     else asm volatile("s_waitcnt vmcnt(0)" ::: "memory");
;     __builtin_amdgcn_s_barrier();
;     asm volatile("" ::: "memory");
;     const bool pf = kt + 3 < nk;
;     const unsigned so = (unsigned)(kt & 3) * GST;
;     bf16x8 a0, a1, a2, a3, b0, b1, b2, b3;
;     asm volatile(
;         "ds_read_b128 %0, %8\n\t"
;         "ds_read_b128 %1, %8 offset:1024\n\t"
;         "ds_read_b128 %2, %8 offset:2048\n\t"
;         "ds_read_b128 %3, %8 offset:3072\n\t"
;         "ds_read_b128 %4, %9\n\t"
;         "ds_read_b128 %5, %9 offset:1024\n\t"
;         "ds_read_b128 %6, %9 offset:2048\n\t"
;         "ds_read_b128 %7, %9 offset:3072\n\t"
;         "s_waitcnt lgkmcnt(0)"
;         : "=&v"(a0), "=&v"(a1), "=&v"(a2), "=&v"(a3), "=&v"(b0), "=&v"(b1), "=&v"(b2), "=&v"(b3)
;         : "v"(lds_a + so), "v"(lds_b + so)
;         : "memory");
;     ...
;     ROW4(accL, 0, a0) ROW4(accL, 1, a1)
;     if (pf) GEMM_DMA_A(kt + 3)
;     ROW4(accL, 2, a2) ROW4(accL, 3, a3)
;     asm volatile(
;         "ds_read_b128 %0, %4 offset:4096\n\t"
;         "ds_read_b128 %1, %4 offset:5120\n\t"
;         "ds_read_b128 %2, %4 offset:6144\n\t"
;         "ds_read_b128 %3, %4 offset:7168\n\t"
;         "s_waitcnt lgkmcnt(0)"
;         : "=&v"(a0), "=&v"(a1), "=&v"(a2), "=&v"(a3)
;         : "v"(lds_a + so)
;         : "memory");
;     ROW4(accH, 0, a0) ROW4(accH, 1, a1)
;     if (pf) GEMM_DMA_B(kt + 3)
;     ROW4(accH, 2, a2) ROW4(accH, 3, a3)
.LBB0_1312:
	s_and_b32 s27, s17, 0x18000
	v_add_u32_e32 v158, s27, v132
	s_add_i32 s27, s17, 0x18000
	s_and_b32 s27, s27, 0x18000
	ds_read_b128 v[232:235], v158 offset:4096
	ds_read_b128 v[236:239], v158 offset:5120
	ds_read_b128 v[240:243], v158 offset:6144
	ds_read_b128 v[244:247], v158 offset:7168
	v_add_u32_e32 v159, s27, v184
	s_waitcnt lgkmcnt(4)
	v_mfma_f32_16x16x32_bf16 v[124:127], v[134:137], v[150:153], v[124:127]
	v_readfirstlane_b32 s27, v159
	s_mov_b32 m0, s27
	s_mov_b64 s[38:39], 0x3bf800c0
	v_mfma_f32_16x16x32_bf16 v[120:123], v[134:137], v[154:157], v[120:123]
	v_mfma_f32_16x16x32_bf16 v[116:119], v[134:137], v[162:165], v[116:119]
	v_mfma_f32_16x16x32_bf16 v[108:111], v[134:137], v[166:169], v[108:111]
	v_lshl_add_u64 v[134:135], v[130:131], 0, s[12:13]
	v_lshl_add_u64 v[136:137], v[134:135], 0, s[28:29]
	v_lshl_add_u64 v[134:135], v[134:135], 0, s[20:21]
	v_mfma_f32_16x16x32_bf16 v[104:107], v[138:141], v[150:153], v[104:107]
	global_load_lds_dwordx4 v[136:137], off
	v_mfma_f32_16x16x32_bf16 v[100:103], v[138:141], v[154:157], v[100:103]
	v_mfma_f32_16x16x32_bf16 v[96:99], v[138:141], v[162:165], v[96:99]
	v_mfma_f32_16x16x32_bf16 v[92:95], v[138:141], v[166:169], v[92:95]
	v_add_u32_e32 v138, 0x2000, v159
	s_nop 0
	v_readfirstlane_b32 s34, v138
	s_mov_b32 m0, s34
	v_mfma_f32_16x16x32_bf16 v[88:91], v[142:145], v[150:153], v[88:91]
	global_load_lds_dwordx4 v[134:135], off
	v_mfma_f32_16x16x32_bf16 v[84:87], v[142:145], v[154:157], v[84:87]
	v_mfma_f32_16x16x32_bf16 v[80:83], v[142:145], v[162:165], v[80:83]
	v_mfma_f32_16x16x32_bf16 v[76:79], v[142:145], v[166:169], v[76:79]
	v_mfma_f32_16x16x32_bf16 v[72:75], v[146:149], v[150:153], v[72:75]
	v_mfma_f32_16x16x32_bf16 v[68:71], v[146:149], v[154:157], v[68:71]
	v_mfma_f32_16x16x32_bf16 v[64:67], v[146:149], v[162:165], v[64:67]
	v_mfma_f32_16x16x32_bf16 v[60:63], v[146:149], v[166:169], v[60:63]
	s_waitcnt lgkmcnt(0)
	s_waitcnt vmcnt(6)
	s_barrier
	s_add_i32 s40, s17, 0x8000
	s_and_b32 s40, s40, 0x18000
	v_add_u32_e32 v198, s40, v132
	v_or_b32_e32 v199, s40, v133
	ds_read_b128 v[200:203], v198
	ds_read_b128 v[204:207], v198 offset:1024
	ds_read_b128 v[208:211], v198 offset:2048
	ds_read_b128 v[212:215], v198 offset:3072
	ds_read_b128 v[216:219], v199
	ds_read_b128 v[220:223], v199 offset:1024
	ds_read_b128 v[224:227], v199 offset:2048
	ds_read_b128 v[228:231], v199 offset:3072
	s_nop 0
	v_mfma_f32_16x16x32_bf16 v[52:55], v[236:239], v[150:153], v[52:55]
	v_mfma_f32_16x16x32_bf16 v[12:15], v[236:239], v[154:157], v[12:15]
	v_mfma_f32_16x16x32_bf16 v[48:51], v[236:239], v[162:165], v[48:51]
	v_mfma_f32_16x16x32_bf16 v[16:19], v[236:239], v[166:169], v[16:19]
	v_add_u32_e32 v138, 0x4000, v159
	v_add_u32_e32 v139, 0x6000, v159
	v_readfirstlane_b32 s27, v138
	v_mfma_f32_16x16x32_bf16 v[112:115], v[232:235], v[150:153], v[112:115]
	v_readfirstlane_b32 s34, v139
	s_mov_b32 m0, s27
	v_mfma_f32_16x16x32_bf16 v[4:7], v[232:235], v[154:157], v[4:7]
	v_mfma_f32_16x16x32_bf16 v[56:59], v[232:235], v[162:165], v[56:59]
	v_mfma_f32_16x16x32_bf16 v[8:11], v[232:235], v[166:169], v[8:11]
	v_lshl_add_u64 v[134:135], v[128:129], 0, s[12:13]
	v_lshl_add_u64 v[136:137], v[134:135], 0, s[38:39]
	s_mov_b64 s[38:39], 0x3bfc00c0
	v_lshl_add_u64 v[134:135], v[134:135], 0, s[38:39]
	global_load_lds_dwordx4 v[136:137], off
	s_mov_b32 m0, s34
	v_mfma_f32_16x16x32_bf16 v[44:47], v[240:243], v[150:153], v[44:47]
	global_load_lds_dwordx4 v[134:135], off
	s_add_u32 s12, s12, 64
	v_mfma_f32_16x16x32_bf16 v[20:23], v[240:243], v[154:157], v[20:23]
	s_addc_u32 s13, s13, 0
	s_add_i32 s17, s17, 0x8000
	s_cmpk_eq_i32 s12, 0x740
	v_mfma_f32_16x16x32_bf16 v[40:43], v[240:243], v[162:165], v[40:43]
	v_mfma_f32_16x16x32_bf16 v[24:27], v[240:243], v[166:169], v[24:27]
	v_mfma_f32_16x16x32_bf16 v[36:39], v[244:247], v[150:153], v[36:39]
	v_mfma_f32_16x16x32_bf16 v[28:31], v[244:247], v[154:157], v[28:31]
	v_mfma_f32_16x16x32_bf16 v[32:35], v[244:247], v[162:165], v[32:35]
	v_mfma_f32_16x16x32_bf16 v[0:3], v[244:247], v[166:169], v[0:3]
	s_waitcnt lgkmcnt(0)
	v_mov_b64_e32 v[134:135], v[200:201]
	v_mov_b64_e32 v[136:137], v[202:203]
	v_mov_b64_e32 v[138:139], v[204:205]
	v_mov_b64_e32 v[140:141], v[206:207]
	v_mov_b64_e32 v[142:143], v[208:209]
	v_mov_b64_e32 v[144:145], v[210:211]
	v_mov_b64_e32 v[146:147], v[212:213]
	v_mov_b64_e32 v[148:149], v[214:215]
	v_mov_b64_e32 v[150:151], v[216:217]
	v_mov_b64_e32 v[152:153], v[218:219]
	v_mov_b64_e32 v[154:155], v[220:221]
	v_mov_b64_e32 v[156:157], v[222:223]
	v_mov_b64_e32 v[162:163], v[224:225]
	v_mov_b64_e32 v[164:165], v[226:227]
	v_mov_b64_e32 v[166:167], v[228:229]
	v_mov_b64_e32 v[168:169], v[230:231]
	s_cbranch_scc0 .LBB0_1312
	s_waitcnt vmcnt(8)
	s_barrier
; #define ROW4(accv, r, av)                                                                              \
;     accv[r][0] = MFMA16(av, b0, accv[r][0]); accv[r][1] = MFMA16(av, b1, accv[r][1]);                      \
;     accv[r][2] = MFMA16(av, b2, accv[r][2]); accv[r][3] = MFMA16(av, b3, accv[r][3]);
; template <int EPI>
; __device__ __forceinline__ void gemm_tile_dma(const bft* __restrict__ A, int lda, const bft* __restrict__ Bt, int K, int row0, int col0,
;                                               char* smem, const EpiArgs& e) {
;     ...
;   for (int kt = 0; kt < nk; ++kt) {
;     if (kt + 2 < nk) asm volatile("s_waitcnt vmcnt(8)" ::: "memory");
;     else if (kt + 1 < nk) asm volatile("s_waitcnt vmcnt(4)" ::: "memory");
;     else asm volatile("s_waitcnt vmcnt(0)" ::: "memory");
;     __builtin_amdgcn_s_barrier();
;     asm volatile("" ::: "memory");
;     const bool pf = kt + 3 < nk;
;     const unsigned so = (unsigned)(kt & 3) * GST;
;     bf16x8 a0, a1, a2, a3, b0, b1, b2, b3;
;     asm volatile(
;         "ds_read_b128 %0, %8\n\t"
;         "ds_read_b128 %1, %8 offset:1024\n\t"
;         "ds_read_b128 %2, %8 offset:2048\n\t"
;         "ds_read_b128 %3, %8 offset:3072\n\t"
;         "ds_read_b128 %4, %9\n\t"
;         "ds_read_b128 %5, %9 offset:1024\n\t"
;         "ds_read_b128 %6, %9 offset:2048\n\t"
;         "ds_read_b128 %7, %9 offset:3072\n\t"
;         "s_waitcnt lgkmcnt(0)"
;         : "=&v"(a0), "=&v"(a1), "=&v"(a2), "=&v"(a3), "=&v"(b0), "=&v"(b1), "=&v"(b2), "=&v"(b3)
;         : "v"(lds_a + so), "v"(lds_b + so)
;         : "memory");
;     ...
;     ROW4(accL, 0, a0) ROW4(accL, 1, a1)
;     if (pf) GEMM_DMA_A(kt + 3)
;     ROW4(accL, 2, a2) ROW4(accL, 3, a3)
;     asm volatile(
;         "ds_read_b128 %0, %4 offset:4096\n\t"
;         "ds_read_b128 %1, %4 offset:5120\n\t"
;         "ds_read_b128 %2, %4 offset:6144\n\t"
;         "ds_read_b128 %3, %4 offset:7168\n\t"
;         "s_waitcnt lgkmcnt(0)"
;         : "=&v"(a0), "=&v"(a1), "=&v"(a2), "=&v"(a3)
;         : "v"(lds_a + so)
;         : "memory");
;     ROW4(accH, 0, a0) ROW4(accH, 1, a1)
;     if (pf) GEMM_DMA_B(kt + 3)
;     ROW4(accH, 2, a2) ROW4(accH, 3, a3)
;     ...
;   }
	v_add_u32_e32 v158, 0x8000, v132
	v_or_b32_e32 v159, 0x8000, v133
	ds_read_b128 v[128:131], v158
	ds_read_b128 v[134:137], v158 offset:1024
	ds_read_b128 v[138:141], v158 offset:2048
	ds_read_b128 v[142:145], v158 offset:3072
	ds_read_b128 v[146:149], v159
	ds_read_b128 v[150:153], v159 offset:1024
	ds_read_b128 v[154:157], v159 offset:2048
	ds_read_b128 v[162:165], v159 offset:3072
	s_waitcnt lgkmcnt(0)
	v_or_b32_e32 v159, 0x10000, v133
	v_mfma_f32_16x16x32_bf16 v[124:127], v[128:131], v[146:149], v[124:127]
	v_add_u32_e32 v178, 0x18000, v132
	v_and_b32_e32 v160, 63, v182
	v_lshrrev_b32_e32 v179, 6, v182
	v_mfma_f32_16x16x32_bf16 v[120:123], v[128:131], v[150:153], v[120:123]
	s_movk_i32 s12, 0x4400
	v_mfma_f32_16x16x32_bf16 v[116:119], v[128:131], v[154:157], v[116:119]
	v_mfma_f32_16x16x32_bf16 v[108:111], v[128:131], v[162:165], v[108:111]
	v_mfma_f32_16x16x32_bf16 v[104:107], v[134:137], v[146:149], v[104:107]
	v_mfma_f32_16x16x32_bf16 v[100:103], v[134:137], v[150:153], v[100:103]
	v_mfma_f32_16x16x32_bf16 v[96:99], v[134:137], v[154:157], v[96:99]
	v_mfma_f32_16x16x32_bf16 v[88:91], v[138:141], v[146:149], v[88:91]
	v_mfma_f32_16x16x32_bf16 v[84:87], v[138:141], v[150:153], v[84:87]
	v_mfma_f32_16x16x32_bf16 v[80:83], v[138:141], v[154:157], v[80:83]
	v_mfma_f32_16x16x32_bf16 v[76:79], v[138:141], v[162:165], v[76:79]
	v_mfma_f32_16x16x32_bf16 v[92:95], v[134:137], v[162:165], v[92:95]
	v_mfma_f32_16x16x32_bf16 v[72:75], v[142:145], v[146:149], v[72:75]
	v_mfma_f32_16x16x32_bf16 v[68:71], v[142:145], v[150:153], v[68:71]
	v_mfma_f32_16x16x32_bf16 v[64:67], v[142:145], v[154:157], v[64:67]
	v_mfma_f32_16x16x32_bf16 v[60:63], v[142:145], v[162:165], v[60:63]
	ds_read_b128 v[128:131], v158 offset:4096
	ds_read_b128 v[134:137], v158 offset:5120
	ds_read_b128 v[138:141], v158 offset:6144
	ds_read_b128 v[142:145], v158 offset:7168
	s_waitcnt lgkmcnt(0)
	s_waitcnt vmcnt(4)
	s_barrier
	v_mfma_f32_16x16x32_bf16 v[112:115], v[128:131], v[146:149], v[112:115]
	v_add_u32_e32 v158, 0x10000, v132
	v_mfma_f32_16x16x32_bf16 v[4:7], v[128:131], v[150:153], v[4:7]
	v_mfma_f32_16x16x32_bf16 v[166:169], v[128:131], v[154:157], v[56:59]
	v_mfma_f32_16x16x32_bf16 v[8:11], v[128:131], v[162:165], v[8:11]
	v_mfma_f32_16x16x32_bf16 v[52:55], v[134:137], v[146:149], v[52:55]
	v_mfma_f32_16x16x32_bf16 v[12:15], v[134:137], v[150:153], v[12:15]
	v_mfma_f32_16x16x32_bf16 v[48:51], v[134:137], v[154:157], v[48:51]
	v_mfma_f32_16x16x32_bf16 v[16:19], v[134:137], v[162:165], v[16:19]
	v_mfma_f32_16x16x32_bf16 v[128:131], v[138:141], v[146:149], v[44:47]
	v_mfma_f32_16x16x32_bf16 v[20:23], v[138:141], v[150:153], v[20:23]
	v_mfma_f32_16x16x32_bf16 v[134:137], v[138:141], v[154:157], v[40:43]
	v_mfma_f32_16x16x32_bf16 v[24:27], v[138:141], v[162:165], v[24:27]
	v_mfma_f32_16x16x32_bf16 v[36:39], v[142:145], v[146:149], v[36:39]
	v_mfma_f32_16x16x32_bf16 v[28:31], v[142:145], v[150:153], v[28:31]
	v_mfma_f32_16x16x32_bf16 v[138:141], v[142:145], v[154:157], v[32:35]
	v_mfma_f32_16x16x32_bf16 v[32:35], v[142:145], v[162:165], v[0:3]
	ds_read_b128 v[0:3], v158
	ds_read_b128 v[56:59], v158 offset:1024
	ds_read_b128 v[142:145], v158 offset:2048
	ds_read_b128 v[146:149], v158 offset:3072
	ds_read_b128 v[150:153], v159
	ds_read_b128 v[44:47], v159 offset:1024
	ds_read_b128 v[154:157], v159 offset:2048
	ds_read_b128 v[40:43], v159 offset:3072
	s_waitcnt lgkmcnt(0)
	s_nop 0
	v_mfma_f32_16x16x32_bf16 v[124:127], v[0:3], v[150:153], v[124:127]
	v_mfma_f32_16x16x32_bf16 v[120:123], v[0:3], v[44:47], v[120:123]
	v_mfma_f32_16x16x32_bf16 v[116:119], v[0:3], v[154:157], v[116:119]
	v_mfma_f32_16x16x32_bf16 v[0:3], v[0:3], v[40:43], v[108:111]
	v_mfma_f32_16x16x32_bf16 v[104:107], v[56:59], v[150:153], v[104:107]
	v_mfma_f32_16x16x32_bf16 v[108:111], v[56:59], v[44:47], v[100:103]
	v_mfma_f32_16x16x32_bf16 v[96:99], v[56:59], v[154:157], v[96:99]
	v_mfma_f32_16x16x32_bf16 v[186:189], v[142:145], v[150:153], v[88:91]
	v_mfma_f32_16x16x32_bf16 v[190:193], v[142:145], v[44:47], v[84:87]
	v_mfma_f32_16x16x32_bf16 v[210:213], v[142:145], v[154:157], v[80:83]
	v_mfma_f32_16x16x32_bf16 v[214:217], v[142:145], v[40:43], v[76:79]
	v_mfma_f32_16x16x32_bf16 v[92:95], v[56:59], v[40:43], v[92:95]
	v_mfma_f32_16x16x32_bf16 v[226:229], v[146:149], v[154:157], v[64:67]
	ds_read_b128 v[84:87], v158 offset:4096
	ds_read_b128 v[76:79], v158 offset:5120
	ds_read_b128 v[64:67], v158 offset:6144
	ds_read_b128 v[56:59], v158 offset:7168
	s_waitcnt lgkmcnt(0)
	s_waitcnt vmcnt(0)
	s_barrier
	v_mfma_f32_16x16x32_bf16 v[218:221], v[146:149], v[150:153], v[72:75]
	v_mfma_f32_16x16x32_bf16 v[222:225], v[146:149], v[44:47], v[68:71]
	v_mfma_f32_16x16x32_bf16 v[230:233], v[146:149], v[40:43], v[60:63]
	v_mfma_f32_16x16x32_bf16 v[234:237], v[84:87], v[150:153], v[112:115]
	v_mfma_f32_16x16x32_bf16 v[238:241], v[76:79], v[150:153], v[52:55]
	v_mfma_f32_16x16x32_bf16 v[68:71], v[76:79], v[154:157], v[48:51]
	v_mfma_f32_16x16x32_bf16 v[242:245], v[64:67], v[150:153], v[128:131]
	v_mfma_f32_16x16x32_bf16 v[246:249], v[56:59], v[150:153], v[36:39]
	s_nop 1
	v_or_b32_e32 v128, 0x18000, v133
	ds_read_b128 v[36:39], v178
	ds_read_b128 v[48:51], v178 offset:1024
	ds_read_b128 v[112:115], v178 offset:2048
	ds_read_b128 v[198:201], v178 offset:3072
	ds_read_b128 v[206:209], v128
	ds_read_b128 v[88:91], v128 offset:1024
	ds_read_b128 v[100:103], v128 offset:2048
	ds_read_b128 v[52:55], v128 offset:3072
	s_waitcnt lgkmcnt(0)
	v_mfma_f32_16x16x32_bf16 v[60:63], v[84:87], v[154:157], v[166:169]
	v_mfma_f32_16x16x32_bf16 v[72:75], v[64:67], v[154:157], v[134:137]
	v_mfma_f32_16x16x32_bf16 v[80:83], v[56:59], v[154:157], v[138:141]
	v_mfma_f32_16x16x32_bf16 v[162:165], v[48:51], v[206:209], v[104:107]
	v_mfma_f32_16x16x32_bf16 v[156:159], v[48:51], v[88:91], v[108:111]
	v_mfma_f32_16x16x32_bf16 v[152:155], v[48:51], v[100:103], v[96:99]
	v_mfma_f32_16x16x32_bf16 v[144:147], v[112:115], v[206:209], v[186:189]
	v_mfma_f32_16x16x32_bf16 v[140:143], v[112:115], v[88:91], v[190:193]
	s_nop 1
	v_mul_lo_u32 v189, v179, s12
	s_mov_b32 s12, 0
	v_mfma_f32_16x16x32_bf16 v[136:139], v[112:115], v[100:103], v[210:213]
	v_bfe_u32 v191, v182, 2, 4
	v_and_b32_e32 v195, 12, v191
	v_mul_u32_u24_e32 v187, 0x110, v195
	v_mfma_f32_16x16x32_bf16 v[132:135], v[112:115], v[52:55], v[214:217]
	ds_read_b128 v[112:115], v178 offset:4096
	ds_read_b128 v[108:111], v178 offset:5120
	ds_read_b128 v[104:107], v178 offset:6144
	ds_read_b128 v[96:99], v178 offset:7168
	s_waitcnt lgkmcnt(0)
	v_and_b32_e32 v178, 0xc0, v182
	v_or_b32_e32 v190, s16, v178
	v_mfma_f32_16x16x32_bf16 v[202:205], v[36:39], v[206:209], v[124:127]
	s_waitcnt vmcnt(0) lgkmcnt(0)
	s_barrier
; template <int EPI>
; DI void epilogue_tile(const EpiArgs& e, int row0, int wrow, int wcol, f32x4 (&acc)[4][4], char* smem, const float* rsm, int wave, int lane,
;                       bool final_sync = true) {
;     ...
;   for (int mi = 0; mi < 4; ++mi)
; #pragma unroll
;     for (int ni = 0; ni < 4; ++ni) {
;       const int lrow = mi * 16 + 4 * g, lcol = ni * 16 + r16;
;       const int col = wcol + lcol;
;       float v[4];
; #pragma unroll
;       for (int j = 0; j < 4; ++j) v[j] = acc[mi][ni][j];
;       if constexpr (EPI == EPI_Q || EPI == EPI_KV) {
; #pragma unroll
;         for (int j = 0; j < 4; ++j) v[j] *= rsm[lrow + j];
;       }
;       if constexpr (EPI == EPI_Q) {
;         const int d = col % 96;
;         if (d >= 64) {
;           const int i = d & 7;
;           const bool second = (d & 8) != 0;
;           const bool colrope = d >= 80;
;           const float inv = exp2f(-(float)i * (13.287712379549449f / 8.f));
; #pragma unroll
;           for (int j = 0; j < 4; ++j) {
;             const float partner = __shfl_xor(v[j], 8);
;             const int nn = n0 + lrow + j;
;             float cs = 1.f, sn = 0.f;
;             if (nn >= CTXL) {
;               const int t = nn - CTXL;
;               const float pos = (float)(colrope ? (t & 63) : (t >> 6));
;               { const float a_ = pos * inv; sn = __sinf(a_); cs = __cosf(a_); }
;             }
;             v[j] = second ? (v[j] * cs + partner * sn) : (v[j] * cs - partner * sn);
;           }
;         }
;       }
;       if constexpr (EPI == EPI_RES) {
;         const float gg = e.gate[(size_t)mi_mod * 6144 + col], bb = e.bias[col];
; #pragma unroll
;         for (int j = 0; j < 4; ++j) v[j] = gg * (v[j] + bb);
;       }
;       if constexpr (EPI == EPI_FF1) {
;         const float bb = e.bias[col];
; #pragma unroll
;         for (int j = 0; j < 4; ++j) { const float t = fmaxf(v[j] + bb, 0.f); v[j] = t * t; }
;       }
;       if (transposed) {
;         *(f32x4*)(stage + lcol * STG + lrow) = (f32x4){v[0], v[1], v[2], v[3]};
;       } else {
; #pragma unroll
;         for (int j = 0; j < 4; ++j) stage[(lrow + j) * STG + lcol] = v[j];
	v_mfma_f32_16x16x32_bf16 v[174:177], v[36:39], v[88:91], v[120:123]
	v_or_b32_e32 v211, 3, v191
	v_mfma_f32_16x16x32_bf16 v[170:173], v[36:39], v[100:103], v[116:119]
	v_mfma_f32_16x16x32_bf16 v[128:131], v[198:201], v[206:209], v[218:221]
	v_mfma_f32_16x16x32_bf16 v[124:127], v[198:201], v[88:91], v[222:225]
	v_mfma_f32_16x16x32_bf16 v[120:123], v[198:201], v[100:103], v[226:229]
	v_mfma_f32_16x16x32_bf16 v[116:119], v[198:201], v[52:55], v[230:233]
	v_or_b32_e32 v198, 48, v160
	v_or_b32_e32 v160, v190, v180
	v_lshlrev_b32_e32 v160, 2, v160
	global_load_dword v193, v160, s[10:11]
	v_lshl_add_u64 v[178:179], s[10:11], 0, v[160:161]
	v_mfma_f32_16x16x32_bf16 v[166:169], v[36:39], v[52:55], v[0:3]
	v_lshl_or_b32 v185, v198, 2, v189
	s_waitcnt vmcnt(0)
	v_add_f32_e32 v186, v204, v193
	v_max_f32_e32 v186, 0, v186
	v_mul_f32_e32 v188, v186, v186
	v_add_f32_e32 v186, v205, v193
	v_add_f32_e32 v160, v202, v193
	v_max_f32_e32 v186, 0, v186
	v_max_f32_e32 v160, 0, v160
	v_add_f32_e32 v181, v203, v193
	v_mul_f32_e32 v194, v186, v186
	v_lshl_or_b32 v186, v180, 2, v189
	v_mul_f32_e32 v160, v160, v160
	v_max_f32_e32 v181, 0, v181
	v_mad_u32_u24 v192, v195, s35, v186
	v_mul_f32_e32 v181, v181, v181
	ds_write_b32 v192, v160
	ds_write_b32 v192, v181 offset:272
	ds_write_b32 v192, v188 offset:544
	v_mad_u32_u24 v199, v211, s35, v186
	v_add_lshl_u32 v160, v190, v180, 2
	ds_write_b32 v199, v194
	global_load_dword v194, v160, s[10:11] offset:64
	v_lshl_add_u64 v[180:181], s[10:11], 0, v[160:161]
	v_mfma_f32_16x16x32_bf16 v[148:151], v[48:51], v[52:55], v[92:95]
	v_add_f32_e32 v162, v162, v193
	v_add_f32_e32 v163, v163, v193
	v_max_f32_e32 v162, 0, v162
	v_max_f32_e32 v163, 0, v163
	v_add_f32_e32 v164, v164, v193
	v_mul_f32_e32 v162, v162, v162
	v_mul_f32_e32 v163, v163, v163
	v_max_f32_e32 v164, 0, v164
	v_add_f32_e32 v165, v165, v193
	v_mul_f32_e32 v164, v164, v164
	v_max_f32_e32 v165, 0, v165
	v_mul_f32_e32 v165, v165, v165
	v_add_f32_e32 v144, v144, v193
	v_add_f32_e32 v145, v145, v193
	v_max_f32_e32 v144, 0, v144
	v_max_f32_e32 v145, 0, v145
	v_add_f32_e32 v146, v146, v193
	v_mul_f32_e32 v144, v144, v144
	v_mul_f32_e32 v145, v145, v145
	v_max_f32_e32 v146, 0, v146
	v_add_f32_e32 v147, v147, v193
	v_mul_f32_e32 v146, v146, v146
	v_max_f32_e32 v147, 0, v147
	v_mul_f32_e32 v147, v147, v147
	v_add_f32_e32 v128, v128, v193
	v_add_f32_e32 v129, v129, v193
	v_max_f32_e32 v128, 0, v128
	v_max_f32_e32 v129, 0, v129
	v_add_f32_e32 v130, v130, v193
	v_mul_f32_e32 v128, v128, v128
	v_mul_f32_e32 v129, v129, v129
	v_max_f32_e32 v130, 0, v130
	v_add_f32_e32 v131, v131, v193
	v_mul_f32_e32 v130, v130, v130
	v_max_f32_e32 v131, 0, v131
	v_mul_f32_e32 v131, v131, v131
	v_mfma_f32_16x16x32_bf16 v[92:95], v[112:115], v[206:209], v[234:237]
	v_mul_u32_u24_e32 v188, 0x110, v211
	s_waitcnt vmcnt(0)
	v_add_f32_e32 v174, v174, v194
	v_max_f32_e32 v174, 0, v174
	v_add_f32_e32 v175, v175, v194
	v_add_f32_e32 v176, v176, v194
	v_add_f32_e32 v177, v177, v194
	v_mul_f32_e32 v174, v174, v174
	v_max_f32_e32 v175, 0, v175
	v_max_f32_e32 v176, 0, v176
	v_max_f32_e32 v177, 0, v177
	v_mul_f32_e32 v175, v175, v175
	v_mul_f32_e32 v176, v176, v176
	v_mul_f32_e32 v177, v177, v177
	ds_write_b32 v192, v174 offset:64
	ds_write_b32 v192, v175 offset:336
	ds_write_b32 v192, v176 offset:608
	ds_write_b32 v199, v177 offset:64
	global_load_dword v174, v160, s[10:11] offset:128
	v_add_f32_e32 v156, v156, v194
	v_max_f32_e32 v156, 0, v156
	v_add_f32_e32 v157, v157, v194
	v_add_f32_e32 v158, v158, v194
	v_add_f32_e32 v159, v159, v194
	v_mul_f32_e32 v156, v156, v156
	v_max_f32_e32 v157, 0, v157
	v_max_f32_e32 v158, 0, v158
	v_max_f32_e32 v159, 0, v159
	v_mul_f32_e32 v157, v157, v157
	v_mul_f32_e32 v158, v158, v158
	v_mul_f32_e32 v159, v159, v159
	v_add_f32_e32 v140, v140, v194
	v_max_f32_e32 v140, 0, v140
	v_add_f32_e32 v141, v141, v194
	v_add_f32_e32 v142, v142, v194
	v_add_f32_e32 v143, v143, v194
	v_mul_f32_e32 v140, v140, v140
	v_max_f32_e32 v141, 0, v141
	v_max_f32_e32 v142, 0, v142
	v_max_f32_e32 v143, 0, v143
	v_mul_f32_e32 v141, v141, v141
	v_mul_f32_e32 v142, v142, v142
	v_mul_f32_e32 v143, v143, v143
	v_add_f32_e32 v124, v124, v194
	v_max_f32_e32 v124, 0, v124
	v_add_f32_e32 v125, v125, v194
	v_add_f32_e32 v126, v126, v194
	v_add_f32_e32 v127, v127, v194
	v_mul_f32_e32 v124, v124, v124
	v_max_f32_e32 v125, 0, v125
	v_max_f32_e32 v126, 0, v126
	v_max_f32_e32 v127, 0, v127
	v_mul_f32_e32 v125, v125, v125
	v_mul_f32_e32 v126, v126, v126
	v_mul_f32_e32 v127, v127, v127
	v_mfma_f32_16x16x32_bf16 v[48:51], v[108:111], v[206:209], v[238:241]
	s_waitcnt vmcnt(0)
; template <int EPI>
; DI void epilogue_tile(const EpiArgs& e, int row0, int wrow, int wcol, f32x4 (&acc)[4][4], char* smem, const float* rsm, int wave, int lane,
;                       bool final_sync = true) {
;     ...
;       if constexpr (EPI == EPI_FF1) {
;         const float bb = e.bias[col];
; #pragma unroll
;         for (int j = 0; j < 4; ++j) { const float t = fmaxf(v[j] + bb, 0.f); v[j] = t * t; }
;       }
;       if (transposed) {
;         *(f32x4*)(stage + lcol * STG + lrow) = (f32x4){v[0], v[1], v[2], v[3]};
;       } else {
; #pragma unroll
;         for (int j = 0; j < 4; ++j) stage[(lrow + j) * STG + lcol] = v[j];
	v_add_f32_e32 v160, v170, v174
	v_max_f32_e32 v160, 0, v160
	v_add_f32_e32 v170, v171, v174
	v_add_f32_e32 v171, v172, v174
	v_add_f32_e32 v172, v173, v174
	v_mul_f32_e32 v160, v160, v160
	v_max_f32_e32 v170, 0, v170
	v_max_f32_e32 v171, 0, v171
	v_max_f32_e32 v172, 0, v172
	v_mul_f32_e32 v170, v170, v170
	v_mul_f32_e32 v171, v171, v171
	v_mul_f32_e32 v172, v172, v172
	ds_write_b32 v192, v160 offset:128
	ds_write_b32 v192, v170 offset:400
	ds_write_b32 v192, v171 offset:672
	ds_write_b32 v199, v172 offset:128
	v_or_b32_e32 v160, v190, v198
	v_lshlrev_b32_e32 v160, 2, v160
	v_lshl_add_u64 v[170:171], s[10:11], 0, v[160:161]
	global_load_dword v160, v160, s[10:11]
	v_mad_u32_u24 v172, v195, s35, v185
	v_add_f32_e32 v152, v152, v174
	v_max_f32_e32 v152, 0, v152
	v_add_f32_e32 v153, v153, v174
	v_add_f32_e32 v154, v154, v174
	v_add_f32_e32 v155, v155, v174
	v_mul_f32_e32 v152, v152, v152
	v_max_f32_e32 v153, 0, v153
	v_max_f32_e32 v154, 0, v154
	v_max_f32_e32 v155, 0, v155
	v_mul_f32_e32 v153, v153, v153
	v_mul_f32_e32 v154, v154, v154
	v_mul_f32_e32 v155, v155, v155
	v_add_f32_e32 v136, v136, v174
	v_max_f32_e32 v136, 0, v136
	v_add_f32_e32 v137, v137, v174
	v_add_f32_e32 v138, v138, v174
	v_add_f32_e32 v139, v139, v174
	v_mul_f32_e32 v136, v136, v136
	v_max_f32_e32 v137, 0, v137
	v_max_f32_e32 v138, 0, v138
	v_max_f32_e32 v139, 0, v139
	v_mul_f32_e32 v137, v137, v137
	v_mul_f32_e32 v138, v138, v138
	v_mul_f32_e32 v139, v139, v139
	v_add_f32_e32 v120, v120, v174
	v_max_f32_e32 v120, 0, v120
	v_add_f32_e32 v121, v121, v174
	v_add_f32_e32 v122, v122, v174
	v_add_f32_e32 v123, v123, v174
	v_mul_f32_e32 v120, v120, v120
	v_max_f32_e32 v121, 0, v121
	v_max_f32_e32 v122, 0, v122
	v_max_f32_e32 v123, 0, v123
	v_mul_f32_e32 v121, v121, v121
	v_mul_f32_e32 v122, v122, v122
	v_mul_f32_e32 v123, v123, v123
	v_mfma_f32_16x16x32_bf16 v[36:39], v[104:107], v[206:209], v[242:245]
	s_waitcnt vmcnt(0)
	v_add_f32_e32 v166, v166, v160
	v_add_f32_e32 v167, v167, v160
	v_max_f32_e32 v166, 0, v166
	v_max_f32_e32 v167, 0, v167
	v_add_f32_e32 v168, v168, v160
	v_add_f32_e32 v169, v169, v160
	v_mul_f32_e32 v166, v166, v166
	v_mul_f32_e32 v167, v167, v167
	v_max_f32_e32 v168, 0, v168
	v_max_f32_e32 v169, 0, v169
	v_mul_f32_e32 v168, v168, v168
	v_mul_f32_e32 v169, v169, v169
	ds_write2_b32 v172, v166, v167 offset1:68
	ds_write_b32 v172, v168 offset:544
	v_mad_u32_u24 v166, v211, s35, v185
	ds_write_b32 v166, v169
	ds_write_b32 v192, v162 offset:4352
	ds_write_b32 v192, v163 offset:4624
	ds_write_b32 v192, v164 offset:4896
	v_or_b32_e32 v163, 19, v191
	v_add_f32_e32 v148, v148, v160
	v_add_f32_e32 v149, v149, v160
	v_mad_u32_u24 v164, v163, s35, v186
	v_max_f32_e32 v148, 0, v148
	v_max_f32_e32 v149, 0, v149
	v_add_f32_e32 v150, v150, v160
	v_add_f32_e32 v151, v151, v160
	ds_write_b32 v164, v165
	ds_write_b32 v192, v156 offset:4416
	ds_write_b32 v192, v157 offset:4688
	ds_write_b32 v192, v158 offset:4960
	ds_write_b32 v164, v159 offset:64
	ds_write_b32 v192, v152 offset:4480
	ds_write_b32 v192, v153 offset:4752
	ds_write_b32 v192, v154 offset:5024
	ds_write_b32 v164, v155 offset:128
	v_mul_f32_e32 v148, v148, v148
	v_mul_f32_e32 v149, v149, v149
	v_max_f32_e32 v150, 0, v150
	v_max_f32_e32 v151, 0, v151
	v_add_u32_e32 v152, 0x1000, v172
	v_mul_f32_e32 v150, v150, v150
	v_mul_f32_e32 v151, v151, v151
	ds_write2_b32 v152, v148, v149 offset0:64 offset1:132
	ds_write_b32 v172, v150 offset:4896
	v_mad_u32_u24 v148, v163, s35, v185
	ds_write_b32 v148, v151
	ds_write_b32 v192, v144 offset:8704
	ds_write_b32 v192, v145 offset:8976
	ds_write_b32 v192, v146 offset:9248
	v_or_b32_e32 v145, 35, v191
	v_add_f32_e32 v132, v132, v160
	v_add_f32_e32 v133, v133, v160
	v_mad_u32_u24 v146, v145, s35, v186
	v_max_f32_e32 v132, 0, v132
	v_max_f32_e32 v133, 0, v133
	v_add_f32_e32 v134, v134, v160
	v_add_f32_e32 v135, v135, v160
	ds_write_b32 v146, v147
	ds_write_b32 v192, v140 offset:8768
	ds_write_b32 v192, v141 offset:9040
	ds_write_b32 v192, v142 offset:9312
	ds_write_b32 v146, v143 offset:64
	ds_write_b32 v192, v136 offset:8832
	ds_write_b32 v192, v137 offset:9104
	ds_write_b32 v192, v138 offset:9376
	ds_write_b32 v146, v139 offset:128
	v_mul_f32_e32 v132, v132, v132
	v_mul_f32_e32 v133, v133, v133
	v_max_f32_e32 v134, 0, v134
	v_max_f32_e32 v135, 0, v135
	v_add_u32_e32 v136, 0x2000, v172
	v_mul_f32_e32 v134, v134, v134
	v_mul_f32_e32 v135, v135, v135
	ds_write2_b32 v136, v132, v133 offset0:128 offset1:196
	ds_write_b32 v172, v134 offset:9248
	v_mad_u32_u24 v132, v145, s35, v185
	ds_write_b32 v132, v135
	ds_write_b32 v192, v128 offset:13056
	ds_write_b32 v192, v129 offset:13328
	ds_write_b32 v192, v130 offset:13600
	v_or_b32_e32 v129, 51, v191
	v_add_f32_e32 v116, v116, v160
	v_add_f32_e32 v117, v117, v160
	v_mad_u32_u24 v130, v129, s35, v186
	v_max_f32_e32 v116, 0, v116
	v_max_f32_e32 v117, 0, v117
	v_add_f32_e32 v118, v118, v160
	v_add_f32_e32 v119, v119, v160
	ds_write_b32 v130, v131
	ds_write_b32 v192, v124 offset:13120
	ds_write_b32 v192, v125 offset:13392
	ds_write_b32 v192, v126 offset:13664
	ds_write_b32 v130, v127 offset:64
	ds_write_b32 v192, v120 offset:13184
	ds_write_b32 v192, v121 offset:13456
	ds_write_b32 v192, v122 offset:13728
	ds_write_b32 v130, v123 offset:128
	v_mul_f32_e32 v116, v116, v116
	v_mul_f32_e32 v117, v117, v117
	v_max_f32_e32 v118, 0, v118
	v_max_f32_e32 v119, 0, v119
	v_add_u32_e32 v120, 0x3200, v172
	v_mul_f32_e32 v118, v118, v118
	v_mul_f32_e32 v119, v119, v119
	ds_write2_b32 v120, v116, v117 offset0:64 offset1:132
	ds_write_b32 v172, v118 offset:13600
	v_mad_u32_u24 v116, v129, s35, v185
	v_mfma_f32_16x16x32_bf16 v[0:3], v[96:99], v[206:209], v[246:249]
	ds_write_b32 v116, v119
	v_bfe_u32 v119, v182, 3, 3
	v_and_b32_e32 v120, 7, v182
	v_lshlrev_b32_e32 v160, 1, v190
	v_add3_u32 v118, v119, s15, v183
	v_mul_u32_u24_e32 v119, 0x110, v119
	v_lshlrev_b32_e32 v120, 5, v120
	v_lshl_add_u64 v[116:117], s[56:57], 0, v[160:161]
	v_and_b32_e32 v160, 0x70, v184
	v_add3_u32 v119, v189, v119, v120
	v_mul_u32_u24_e32 v162, 0x110, v163
	v_mul_u32_u24_e32 v144, 0x110, v145
	v_mul_u32_u24_e32 v128, 0x110, v129
	v_lshl_add_u64 v[116:117], v[116:117], 0, v[160:161]
	v_mov_b32_e32 v120, v119
